# key-split attention item made seamless: the barrier sits before the last tile of an interval is consumed, so QK^T of the next interval's first tile overlaps the softmax / P.V of the previous tile (no
# speedup vs baseline: 1.1156x; 1.0125x over previous
; DI int get_tid() { int t = threadIdx.x; asm volatile("" : "+v"(t)); return t; }
; template <bool NA, bool TRACK>
; DI void attn_item(char* lds, const bf16_t* P, bf16_t* Y, const bf16_t* vt, int rp, int q_off, int k1_off, int nt1,
;                   int vk1, int k2_off, int nt2, int vk2, int g_off, int y_off, int rlo, const float* rpb) {
;   asm volatile("" : "+v"(q_off), "+v"(g_off), "+v"(y_off));
;   const bf16_t* qp = P + q_off;
;   const bf16_t* kp1 = P + k1_off;
;   const bf16_t* kp2 = P + k2_off;
;   const int tid = get_tid(), lane = tid & 63, w = tid >> 6, r = lane & 31, h = lane >> 5;
;   const int lr = tid >> 3, lc = tid & 7;
;   const int nt = nt1 + nt2;
;   const int woff = lr * 128 + ((lc ^ ((lr >> 1) & 7)) << 4);
;   const int swz = (r >> 1) & 7;
;   float* tab = (float*)(lds + 131072);
;   int rw = 0, r0w = 0, cq = 0, c0 = 0;
;   if (NA) {
;     rw = rp * 4 + (w >> 1);
;     r0w = clampi(rw - 4, 0, 24);
;     cq = (w & 1) * 32 + r;
;     c0 = clampi(cq - 8, 0, 48);
;     for (int e = tid; e < 15 * 128; e += NTHREADS) {
;       const int dr = e >> 7, dc = (e & 127) - 48;
;       tab[e] = (dc >= 0 && dc < 31) ? rpb[dr * 31 + dc] * LOG2E : 0.f;
;     }
;   }
;   bf16x8 qf[4];
; #pragma unroll
;   for (int ks = 0; ks < 4; ++ks) qf[ks] = *(const bf16x8*)(qp + (size_t)(w * 32 + r) * INW + ks * 16 + h * 8);
;   u32x2 gate[2][4];
; #pragma unroll
;   for (int dm = 0; dm < 2; ++dm)
; #pragma unroll
;     for (int g = 0; g < 4; ++g)
;       gate[dm][g] = *(const u32x2*)(P + g_off + (size_t)(w * 32 + r) * INW + dm * 32 + 8 * g + 4 * h);
; #pragma unroll
;   for (int ks = 0; ks < 4; ++ks) asm volatile("" : "+v"(qf[ks]));
; #pragma unroll
;   for (int dm = 0; dm < 2; ++dm)
; #pragma unroll
;     for (int g = 0; g < 4; ++g) asm volatile("" : "+v"(gate[dm][g]));
;   f32x16 o[2];
;   o[0] = zero16(); o[1] = zero16();
;   f32x16 negm;
; #pragma unroll
;   for (int i = 0; i < 16; ++i) negm[i] = 0.f;
;   float l_run = 0.f;
;   constexpr int TPI = 4;
;   const int niter = (nt + TPI - 1) / TPI;
;   u32x4 rk[TPI], rv[TPI];
;     ...
;   ATT_LOAD(0);
;   ATT_WRITE(0, 0);
;   __syncthreads();
.LBB0_109:
	s_lshl_b32 s3, s25, 6
	s_add_i32 s12, s3, 0x700
	s_and_b64 s[8:9], s[4:5], exec
	s_cselect_b32 s26, s12, s3
	s_lshl_b32 s10, s10, 6
	s_and_b64 s[8:9], s[4:5], exec
	s_movk_i32 s8, 0x800
	s_cselect_b32 s8, s8, 0x200
	s_add_i32 s13, s8, s10
	s_add_i32 s8, s3, 0xa00
	s_add_i32 s9, s3, 0x300
	s_and_b64 s[4:5], s[4:5], exec
	v_readlane_b32 s36, v254, 41
	s_cselect_b32 s28, s9, s3
	s_cselect_b32 s3, 8, 7
	v_readlane_b32 s46, v254, 51
	v_readlane_b32 s47, v254, 52
	v_readlane_b32 s48, v254, 53
	v_readlane_b32 s49, v254, 54
	s_cselect_b32 s27, s8, s9
	s_cselect_b32 s4, s49, s47
	s_cselect_b32 s5, s48, s46
	s_lshl_b32 s3, s0, s3
	s_add_i32 s3, s3, s10
	s_mul_hi_i32 s9, s3, 0x1200
	s_mulk_i32 s3, 0x1200
	s_add_u32 s8, s5, s3
	s_mul_i32 s0, s0, 0xb0000
	s_addc_u32 s9, s4, s9
	s_add_i32 s0, s0, s13
	s_mul_i32 s3, s11, 0xb00
	s_mulk_i32 s2, 0xb00
	s_add_i32 s10, s0, 0x5800000
	s_lshl_b32 s0, s11, 10
	s_add_i32 s26, s26, s3
	s_add_i32 s12, s13, s2
	s_add_i32 s27, s27, s3
	s_add_i32 s28, s28, s0
	s_andn2_b64 vcc, exec, s[6:7]
	s_mov_b64 s[2:3], -1
	v_readlane_b32 s37, v254, 42
	v_readlane_b32 s38, v254, 43
	v_readlane_b32 s39, v254, 44
	v_readlane_b32 s40, v254, 45
	v_readlane_b32 s41, v254, 46
	v_readlane_b32 s42, v254, 47
	v_readlane_b32 s43, v254, 48
	v_readlane_b32 s44, v254, 49
	v_readlane_b32 s45, v254, 50
	v_readlane_b32 s50, v254, 55
	v_readlane_b32 s51, v254, 56
	s_cbranch_vccz .LBB0_184
	v_readlane_b32 s4, v255, 10
	v_readlane_b32 s5, v255, 11
	s_ashr_i32 s13, s12, 31
	s_ashr_i32 s11, s10, 31
	s_and_b64 vcc, exec, s[4:5]
	s_cbranch_vccz .LBB0_156
	v_readlane_b32 s44, v254, 49
	v_readlane_b32 s45, v254, 50
	s_mov_b32 s34, s26
	s_ashr_i32 s35, s26, 31
	s_lshl_b64 s[34:35], s[34:35], 1
	s_add_u32 s34, s34, s44
	s_addc_u32 s35, s35, s45
	s_mov_b32 s36, s27
	s_ashr_i32 s37, s27, 31
	s_lshl_b64 s[36:37], s[36:37], 1
	s_add_u32 s36, s36, s44
	s_addc_u32 s37, s37, s45
	s_lshl_b64 s[4:5], s[12:13], 1
	s_add_u32 s4, s4, s44
	s_addc_u32 s5, s5, s45
	s_lshl_b64 s[6:7], s[10:11], 1
	s_add_u32 s6, s6, s44
	s_addc_u32 s7, s7, s45
	s_add_i32 s19, s79, 4
	s_lshr_b32 s19, s19, 2
	s_mov_b32 s18, 0
	s_add_u32 s46, s34, 0x2c000
	s_addc_u32 s47, s35, 0
	v_lshrrev_b32_e32 v0, 6, v251
	s_nop 0
	v_readfirstlane_b32 s38, v0
	s_nop 3
	s_lshl_b32 s30, s38, 10
	s_mul_i32 s39, s38, 0x2400
	s_xor_b32 s40, s38, 1
	s_mul_i32 s40, s40, 0x2400
	s_and_b32 s38, s38, 1
	v_lshrrev_b32_e32 v225, 7, v251
	v_and_b32_e32 v226, 31, v251
	v_lshl_or_b32 v225, v225, 6, v226
	v_bfe_u32 v227, v251, 5, 1
	v_mul_u32_u24_e32 v225, 0x1600, v225
	v_lshl_add_u32 v224, v227, 4, v225
	global_load_dwordx4 v[130:133], v224, s[34:35]
	global_load_dwordx4 v[134:137], v224, s[34:35] offset:32
	global_load_dwordx4 v[138:141], v224, s[34:35] offset:64
	global_load_dwordx4 v[142:145], v224, s[34:35] offset:96
	global_load_dwordx4 v[146:149], v224, s[46:47]
	global_load_dwordx4 v[150:153], v224, s[46:47] offset:32
	global_load_dwordx4 v[154:157], v224, s[46:47] offset:64
	global_load_dwordx4 v[158:161], v224, s[46:47] offset:96
	v_lshrrev_b32_e32 v0, 3, v251
	v_and_b32_e32 v225, 7, v251
	v_bfe_u32 v226, v251, 4, 3
	v_xor_b32_e32 v225, v225, v226
	v_mul_u32_u24_e32 v222, 0x1600, v0
	v_lshl_add_u32 v222, v225, 4, v222
	v_mul_u32_u24_e32 v223, 0x1200, v0
	v_lshl_add_u32 v223, v225, 4, v223
	s_mov_b32 s20, 0
	s_and_b32 s31, s20, 1
	s_lshl_b32 s31, s31, 16
	s_add_u32 s31, s31, s30
	s_lshl_b32 s20, s20, 2
	s_cmp_lt_i32 s20, s79
	s_cselect_b32 s21, 0, s79
	s_cselect_b32 s22, s4, s6
	s_cselect_b32 s23, s5, s7
	s_cselect_b32 s29, s90, 0x800
	s_sub_i32 s20, s20, s21
	s_mul_i32 s21, s20, 0x58000
	s_add_u32 s14, s22, s21
	s_addc_u32 s15, s23, 0
	s_lshl_b32 s20, s20, 6
	s_add_i32 s20, s20, s29
	s_lshl_b32 s20, s20, 1
	s_add_u32 s16, s8, s20
	s_addc_u32 s17, s9, 0
	s_add_u32 m0, s31, 0x0
	s_nop 0
	global_load_lds_dwordx4 v222, s[14:15]
	s_add_u32 m0, s31, 0x2000
	s_nop 0
	global_load_lds_dwordx4 v223, s[16:17]
	s_add_u32 s14, s14, 0x58000
	s_addc_u32 s15, s15, 0
	s_add_u32 s16, s16, 0x80
	s_addc_u32 s17, s17, 0
	s_add_u32 m0, s31, 0x4000
	s_nop 0
	global_load_lds_dwordx4 v222, s[14:15]
	s_add_u32 m0, s31, 0x6000
	s_nop 0
	global_load_lds_dwordx4 v223, s[16:17]
	s_add_u32 s14, s14, 0x58000
	s_addc_u32 s15, s15, 0
	s_add_u32 s16, s16, 0x80
	s_addc_u32 s17, s17, 0
	s_add_u32 m0, s31, 0x8000
	s_nop 0
	global_load_lds_dwordx4 v222, s[14:15]
	s_add_u32 m0, s31, 0xa000
	s_nop 0
	global_load_lds_dwordx4 v223, s[16:17]
	s_add_u32 s14, s14, 0x58000
	s_addc_u32 s15, s15, 0
	s_add_u32 s16, s16, 0x80
	s_addc_u32 s17, s17, 0
	s_add_u32 m0, s31, 0xc000
	s_nop 0
	global_load_lds_dwordx4 v222, s[14:15]
	s_add_u32 m0, s31, 0xe000
	s_nop 0
	global_load_lds_dwordx4 v223, s[16:17]
	v_and_b32_e32 v0, 31, v251
	v_lshlrev_b32_e32 v0, 7, v0
	v_bfe_u32 v225, v251, 1, 3
	v_xor_b32_e32 v225, v225, v227
	v_bfe_u32 v226, v251, 6, 1
	v_lshl_or_b32 v228, v226, 12, v0
	v_lshl_or_b32 v216, v225, 4, v228
	v_xor_b32_e32 v229, 2, v225
	v_lshl_or_b32 v217, v229, 4, v228
	v_xor_b32_e32 v229, 4, v225
	v_lshl_or_b32 v218, v229, 4, v228
	v_xor_b32_e32 v229, 6, v225
	v_lshl_or_b32 v219, v229, 4, v228
	v_lshlrev_b32_e32 v226, 2, v226
	v_xor_b32_e32 v225, v225, v226
	v_lshl_or_b32 v220, v225, 4, v0
	v_xor_b32_e32 v229, 2, v225
	v_lshl_or_b32 v221, v229, 4, v0
	v_ashrrev_i32_e32 v0, 1, v251
	s_movk_i32 s0, 0xffe0
	v_bfi_b32 v0, s0, v0, v251
	v_mul_u32_u24_e32 v0, 0x1600, v0
	v_lshl_add_u32 v0, v227, 3, v0
	global_load_dwordx2 v[232:233], v0, s[36:37]
	global_load_dwordx2 v[234:235], v0, s[36:37] offset:16
	global_load_dwordx2 v[236:237], v0, s[36:37] offset:32
	global_load_dwordx2 v[238:239], v0, s[36:37] offset:48
	global_load_dwordx2 v[242:243], v0, s[36:37] offset:64
; #define ATT_WRITE(IT, HALF) do { _Pragma("unroll") for (int j_ = 0; j_ < TPI; ++j_) { const int t_ = (IT) * TPI + j_; if (t_ < nt) { \
;       char* sl_ = lds + (HALF) * 65536 + j_ * 16384; \
;       *(u32x4*)(sl_ + woff) = rk[j_]; \
;       *(u32x4*)(sl_ + 8192 + woff) = rv[j_]; } } } while (0)
; template <bool NA, bool TRACK>
; DI void attn_item(char* lds, const bf16_t* P, bf16_t* Y, const bf16_t* vt, int rp, int q_off, int k1_off, int nt1,
;                   int vk1, int k2_off, int nt2, int vk2, int g_off, int y_off, int rlo, const float* rpb) {
;     ...
;       gate[dm][g] = *(const u32x2*)(P + g_off + (size_t)(w * 32 + r) * INW + dm * 32 + 8 * g + 4 * h);
; #pragma unroll
;   for (int ks = 0; ks < 4; ++ks) asm volatile("" : "+v"(qf[ks]));
; #pragma unroll
;   for (int dm = 0; dm < 2; ++dm)
; #pragma unroll
;     for (int g = 0; g < 4; ++g) asm volatile("" : "+v"(gate[dm][g]));
;   f32x16 o[2];
;   o[0] = zero16(); o[1] = zero16();
;   f32x16 negm;
; #pragma unroll
;   for (int i = 0; i < 16; ++i) negm[i] = 0.f;
;   float l_run = 0.f;
;   constexpr int TPI = 4;
;   const int niter = (nt + TPI - 1) / TPI;
;   u32x4 rk[TPI], rv[TPI];
;     ...
;   ATT_LOAD(0);
;   ATT_WRITE(0, 0);
;   __syncthreads();
;   for (int it = 0; it < niter; ++it) {
;     const int hb = it & 1;
;     if constexpr (NA || TRACK) { if (it + 1 < niter) ATT_LOAD(it + 1); }
;     if constexpr (!NA && !TRACK) {
;     ...
;       const bool more = it + 1 < niter;
;       if (more) ATT_LOAD2(it + 1, 0);
;       const char* Kb = lds + hb * 65536;
;       f32x16 sc[2], sn[2];
;     ...
;       ATT_QK(sc, 0);
; #pragma unroll
;       for (int j = 0; j < TPI; ++j) {
;         const char* Vs = Kb + j * 16384 + 8192;
;         if (j + 1 < TPI) ATT_QK(sn, j + 1);
	global_load_dwordx2 v[244:245], v0, s[36:37] offset:80
	global_load_dwordx2 v[226:227], v0, s[36:37] offset:96
	global_load_dwordx2 v[224:225], v0, s[36:37] offset:112
	v_mov_b32_e32 v2, 0
	v_mov_b32_e32 v3, 0
	v_mov_b32_e32 v4, 0
	v_mov_b32_e32 v5, 0
	v_mov_b32_e32 v6, 0
	v_mov_b32_e32 v7, 0
	v_mov_b32_e32 v8, 0
	v_mov_b32_e32 v9, 0
	v_mov_b32_e32 v10, 0
	v_mov_b32_e32 v11, 0
	v_mov_b32_e32 v12, 0
	v_mov_b32_e32 v13, 0
	v_mov_b32_e32 v14, 0
	v_mov_b32_e32 v15, 0
	v_mov_b32_e32 v16, 0
	v_mov_b32_e32 v17, 0
	v_mov_b32_e32 v18, 0
	v_mov_b32_e32 v19, 0
	v_mov_b32_e32 v20, 0
	v_mov_b32_e32 v21, 0
	v_mov_b32_e32 v22, 0
	v_mov_b32_e32 v23, 0
	v_mov_b32_e32 v24, 0
	v_mov_b32_e32 v25, 0
	v_mov_b32_e32 v26, 0
	v_mov_b32_e32 v27, 0
	v_mov_b32_e32 v28, 0
	v_mov_b32_e32 v29, 0
	v_mov_b32_e32 v30, 0
	v_mov_b32_e32 v31, 0
	v_mov_b32_e32 v32, 0
	v_mov_b32_e32 v33, 0
	v_mov_b32_e32 v34, 0
	v_mov_b32_e32 v35, 0
	v_mov_b32_e32 v36, 0
	v_mov_b32_e32 v37, 0
	v_mov_b32_e32 v38, 0
	v_mov_b32_e32 v39, 0
	v_mov_b32_e32 v40, 0
	v_mov_b32_e32 v41, 0
	v_mov_b32_e32 v42, 0
	v_mov_b32_e32 v43, 0
	v_mov_b32_e32 v44, 0
	v_mov_b32_e32 v45, 0
	v_mov_b32_e32 v46, 0
	v_mov_b32_e32 v47, 0
	v_mov_b32_e32 v48, 0
	v_mov_b32_e32 v49, 0
	v_mov_b32_e32 v50, 0
	v_mov_b32_e32 v51, 0
	v_mov_b32_e32 v52, 0
	v_mov_b32_e32 v53, 0
	v_mov_b32_e32 v54, 0
	v_mov_b32_e32 v55, 0
	v_mov_b32_e32 v56, 0
	v_mov_b32_e32 v57, 0
	v_mov_b32_e32 v58, 0
	v_mov_b32_e32 v59, 0
	v_mov_b32_e32 v60, 0
	v_mov_b32_e32 v61, 0
	v_mov_b32_e32 v62, 0
	v_mov_b32_e32 v63, 0
	v_mov_b32_e32 v64, 0
	v_mov_b32_e32 v65, 0
	v_mov_b32_e32 v212, 0
	v_mov_b32_e32 v213, 0
	v_mov_b32_e32 v214, 0
	v_mov_b32_e32 v215, 0
	s_waitcnt vmcnt(8)
	s_barrier
	ds_read_b128 v[162:165], v216
	ds_read_b128 v[166:169], v217
	ds_read_b128 v[170:173], v218
	ds_read_b128 v[174:177], v219
	s_add_i32 s20, s18, 1
	s_cmp_ge_i32 s20, s19
	s_cbranch_scc1 .Ldk_skip_pro
	s_and_b32 s31, s20, 1
	s_lshl_b32 s31, s31, 16
	s_add_u32 s31, s31, s30
	s_lshl_b32 s20, s20, 2
	s_cmp_lt_i32 s20, s79
	s_cselect_b32 s21, 0, s79
	s_cselect_b32 s22, s4, s6
	s_cselect_b32 s23, s5, s7
	s_cselect_b32 s29, s90, 0x800
	s_sub_i32 s20, s20, s21
	s_mul_i32 s21, s20, 0x58000
	s_add_u32 s14, s22, s21
	s_addc_u32 s15, s23, 0
	s_lshl_b32 s20, s20, 6
	s_add_i32 s20, s20, s29
	s_lshl_b32 s20, s20, 1
	s_add_u32 s16, s8, s20
	s_addc_u32 s17, s9, 0
	s_add_u32 m0, s31, 0x0
	s_nop 0
	global_load_lds_dwordx4 v222, s[14:15]
	s_add_u32 m0, s31, 0x2000
	s_nop 0
	global_load_lds_dwordx4 v223, s[16:17]
	s_add_u32 s14, s14, 0x58000
	s_addc_u32 s15, s15, 0
	s_add_u32 s16, s16, 0x80
	s_addc_u32 s17, s17, 0
	s_add_u32 m0, s31, 0x4000
	s_nop 0
	global_load_lds_dwordx4 v222, s[14:15]
	s_add_u32 m0, s31, 0x6000
	s_nop 0
	global_load_lds_dwordx4 v223, s[16:17]
	s_add_u32 s14, s14, 0x58000
	s_addc_u32 s15, s15, 0
	s_add_u32 s16, s16, 0x80
	s_addc_u32 s17, s17, 0
	s_add_u32 m0, s31, 0x8000
	s_nop 0
	global_load_lds_dwordx4 v222, s[14:15]
	s_add_u32 m0, s31, 0xa000
	s_nop 0
	global_load_lds_dwordx4 v223, s[16:17]
	s_add_u32 s14, s14, 0x58000
	s_addc_u32 s15, s15, 0
	s_add_u32 s16, s16, 0x80
	s_addc_u32 s17, s17, 0
	s_add_u32 m0, s31, 0xc000
	s_nop 0
	global_load_lds_dwordx4 v222, s[14:15]
	s_add_u32 m0, s31, 0xe000
	s_nop 0
	global_load_lds_dwordx4 v223, s[16:17]
.Ldk_skip_pro:
	s_waitcnt lgkmcnt(3)
	v_mfma_f32_32x32x16_bf16 v[66:81], v[162:165], v[130:133], 0
	v_mfma_f32_32x32x16_bf16 v[82:97], v[162:165], v[146:149], 0
	ds_read_b128 v[162:165], v216 offset:16384
	s_waitcnt lgkmcnt(3)
	v_mfma_f32_32x32x16_bf16 v[66:81], v[166:169], v[134:137], v[66:81]
	v_mfma_f32_32x32x16_bf16 v[82:97], v[166:169], v[150:153], v[82:97]
	ds_read_b128 v[166:169], v217 offset:16384
	s_waitcnt lgkmcnt(3)
	v_mfma_f32_32x32x16_bf16 v[66:81], v[170:173], v[138:141], v[66:81]
	v_mfma_f32_32x32x16_bf16 v[82:97], v[170:173], v[154:157], v[82:97]
	ds_read_b128 v[170:173], v218 offset:16384
	s_waitcnt lgkmcnt(3)
	v_mfma_f32_32x32x16_bf16 v[66:81], v[174:177], v[142:145], v[66:81]
	v_mfma_f32_32x32x16_bf16 v[82:97], v[174:177], v[158:161], v[82:97]
	ds_read_b128 v[174:177], v219 offset:16384
	ds_read_b128 v[178:181], v220 offset:8192
	ds_read_b128 v[182:185], v220 offset:12288
	ds_read_b128 v[186:189], v221 offset:8192
	ds_read_b128 v[192:195], v221 offset:12288
	s_nop 7
	s_nop 3
	v_exp_f32_e32 v66, v66
	v_exp_f32_e32 v67, v67
	v_exp_f32_e32 v68, v68
	v_exp_f32_e32 v69, v69
	v_cvt_pk_bf16_f32 v196, v66, v67
	v_add_f32_e32 v212, v212, v66
	v_add_f32_e32 v213, v213, v67
	v_exp_f32_e32 v70, v70
	v_exp_f32_e32 v71, v71
	v_cvt_pk_bf16_f32 v197, v68, v69
	v_add_f32_e32 v212, v212, v68
	v_add_f32_e32 v213, v213, v69
	v_exp_f32_e32 v72, v72
	v_exp_f32_e32 v73, v73
	v_add_f32_e32 v212, v212, v70
	v_add_f32_e32 v213, v213, v71
	v_cvt_pk_bf16_f32 v198, v70, v71
	v_add_f32_e32 v212, v212, v72
	v_add_f32_e32 v213, v213, v73
	v_cvt_pk_bf16_f32 v199, v72, v73
	s_nop 1
; DI f32x16 mfma32(bf16x8 a, bf16x8 b, f32x16 c) { return __builtin_amdgcn_mfma_f32_32x32x16_bf16(a, b, c, 0, 0, 0); }
; DI float fast_exp2(float x) { return __builtin_amdgcn_exp2f(x); }
; #define ATT_WRITE2(HALF, H) do { _Pragma("unroll") for (int j_ = 0; j_ < 2; ++j_) { \
;       char* sl_ = lds + (HALF) * 65536 + (2 * (H) + j_) * 16384; \
;       *(u32x4*)(sl_ + woff) = rk[j_]; \
;       *(u32x4*)(sl_ + 8192 + woff) = rv[j_]; } } while (0)
; template <bool NA, bool TRACK>
; DI void attn_item(char* lds, const bf16_t* P, bf16_t* Y, const bf16_t* vt, int rp, int q_off, int k1_off, int nt1,
;                   int vk1, int k2_off, int nt2, int vk2, int g_off, int y_off, int rlo, const float* rpb) {
;     ...
;       for (int j = 0; j < TPI; ++j) {
;         const char* Vs = Kb + j * 16384 + 8192;
;         if (j + 1 < TPI) ATT_QK(sn, j + 1);
;         float ps = 0.f;
; #pragma unroll
;         for (int kt = 0; kt < 2; ++kt) {
;           bf16x8 vf[4];
; #pragma unroll
;           for (int sp = 0; sp < 2; ++sp)
; #pragma unroll
;             for (int dm = 0; dm < 2; ++dm)
;               vf[sp * 2 + dm] = *(const bf16x8*)(Vs + (dm * 32 + r) * 128 + (((4 * kt + 2 * sp + h) ^ swz) << 4));
; #pragma unroll
;           for (int i = 0; i < 16; ++i) {
;             const float pv = fast_exp2(sc[kt][i]);
;             ps += pv;
;             sc[kt][i] = pv;
;           }
; #pragma unroll
;           for (int sp = 0; sp < 2; ++sp) {
;             u32x4 pu;
;             pu[0] = pk2(sc[kt][8 * sp + 0], sc[kt][8 * sp + 1]);
;             pu[1] = pk2(sc[kt][8 * sp + 2], sc[kt][8 * sp + 3]);
;             pu[2] = pk2(sc[kt][8 * sp + 4], sc[kt][8 * sp + 5]);
;             pu[3] = pk2(sc[kt][8 * sp + 6], sc[kt][8 * sp + 7]);
;             const bf16x8 pf = __builtin_bit_cast(bf16x8, pu);
; #pragma unroll
;             for (int dm = 0; dm < 2; ++dm) o[dm] = mfma32(vf[sp * 2 + dm], pf, o[dm]);
;           }
;         }
;         l_run += ps;
;         if (j + 1 < TPI) { sc[0] = sn[0]; sc[1] = sn[1]; }
;         if (j == 1 && more) { ATT_WRITE2(hb ^ 1, 0); ATT_LOAD2(it + 1, 1); }
;       }
.Ldk_loop:
	s_waitcnt lgkmcnt(7)
	v_mfma_f32_32x32x16_bf16 v[98:113], v[162:165], v[130:133], 0
	v_exp_f32_e32 v74, v74
	v_exp_f32_e32 v75, v75
	v_exp_f32_e32 v76, v76
	v_mfma_f32_32x32x16_bf16 v[114:129], v[162:165], v[146:149], 0
	ds_read_b128 v[162:165], v216 offset:32768
	v_exp_f32_e32 v77, v77
	v_cvt_pk_bf16_f32 v200, v74, v75
	v_add_f32_e32 v212, v212, v74
	v_add_f32_e32 v213, v213, v75
	v_exp_f32_e32 v78, v78
	s_waitcnt lgkmcnt(7)
	v_mfma_f32_32x32x16_bf16 v[98:113], v[166:169], v[134:137], v[98:113]
	v_exp_f32_e32 v79, v79
	v_cvt_pk_bf16_f32 v201, v76, v77
	v_add_f32_e32 v212, v212, v76
	v_add_f32_e32 v213, v213, v77
	v_exp_f32_e32 v80, v80
	v_mfma_f32_32x32x16_bf16 v[114:129], v[166:169], v[150:153], v[114:129]
	ds_read_b128 v[166:169], v217 offset:32768
	v_exp_f32_e32 v81, v81
	v_add_f32_e32 v212, v212, v78
	v_add_f32_e32 v213, v213, v79
	v_cvt_pk_bf16_f32 v202, v78, v79
	v_add_f32_e32 v212, v212, v80
	v_add_f32_e32 v213, v213, v81
	v_cvt_pk_bf16_f32 v203, v80, v81
	s_waitcnt lgkmcnt(5)
	v_mfma_f32_32x32x16_bf16 v[18:33], v[178:181], v[196:199], v[18:33]
	v_exp_f32_e32 v82, v82
	v_exp_f32_e32 v83, v83
	v_exp_f32_e32 v84, v84
	s_waitcnt lgkmcnt(4)
	v_mfma_f32_32x32x16_bf16 v[2:17], v[182:185], v[196:199], v[2:17]
	v_exp_f32_e32 v85, v85
	v_cvt_pk_bf16_f32 v204, v82, v83
	v_add_f32_e32 v214, v214, v82
	v_add_f32_e32 v215, v215, v83
	v_exp_f32_e32 v86, v86
	s_waitcnt lgkmcnt(3)
	v_mfma_f32_32x32x16_bf16 v[18:33], v[186:189], v[200:203], v[18:33]
	v_exp_f32_e32 v87, v87
	v_cvt_pk_bf16_f32 v205, v84, v85
	v_add_f32_e32 v214, v214, v84
	v_add_f32_e32 v215, v215, v85
	v_exp_f32_e32 v88, v88
	s_waitcnt lgkmcnt(2)
	v_mfma_f32_32x32x16_bf16 v[2:17], v[192:195], v[200:203], v[2:17]
	v_exp_f32_e32 v89, v89
	v_add_f32_e32 v214, v214, v86
	v_add_f32_e32 v215, v215, v87
	v_cvt_pk_bf16_f32 v206, v86, v87
	v_add_f32_e32 v214, v214, v88
	v_add_f32_e32 v215, v215, v89
	v_cvt_pk_bf16_f32 v207, v88, v89
	v_mfma_f32_32x32x16_bf16 v[98:113], v[170:173], v[138:141], v[98:113]
	v_exp_f32_e32 v90, v90
	v_exp_f32_e32 v91, v91
	v_exp_f32_e32 v92, v92
	v_mfma_f32_32x32x16_bf16 v[114:129], v[170:173], v[154:157], v[114:129]
	ds_read_b128 v[170:173], v218 offset:32768
	v_exp_f32_e32 v93, v93
	v_cvt_pk_bf16_f32 v208, v90, v91
	v_add_f32_e32 v214, v214, v90
	v_add_f32_e32 v215, v215, v91
	v_exp_f32_e32 v94, v94
	v_mfma_f32_32x32x16_bf16 v[98:113], v[174:177], v[142:145], v[98:113]
	v_exp_f32_e32 v95, v95
	v_cvt_pk_bf16_f32 v209, v92, v93
	v_add_f32_e32 v214, v214, v92
	v_add_f32_e32 v215, v215, v93
	v_exp_f32_e32 v96, v96
	v_mfma_f32_32x32x16_bf16 v[114:129], v[174:177], v[158:161], v[114:129]
	ds_read_b128 v[174:177], v219 offset:32768
	v_exp_f32_e32 v97, v97
	v_add_f32_e32 v214, v214, v94
	v_add_f32_e32 v215, v215, v95
	v_cvt_pk_bf16_f32 v210, v94, v95
	v_add_f32_e32 v214, v214, v96
	v_add_f32_e32 v215, v215, v97
	v_cvt_pk_bf16_f32 v211, v96, v97
	v_mfma_f32_32x32x16_bf16 v[50:65], v[178:181], v[204:207], v[50:65]
	s_nop 1
	v_exp_f32_e32 v98, v98
	v_exp_f32_e32 v99, v99
	v_exp_f32_e32 v100, v100
	v_mfma_f32_32x32x16_bf16 v[34:49], v[182:185], v[204:207], v[34:49]
	ds_read_b128 v[178:181], v220 offset:24576
	ds_read_b128 v[182:185], v220 offset:28672
	v_exp_f32_e32 v101, v101
	v_cvt_pk_bf16_f32 v196, v98, v99
	v_add_f32_e32 v212, v212, v98
	v_add_f32_e32 v213, v213, v99
	v_exp_f32_e32 v102, v102
	v_mfma_f32_32x32x16_bf16 v[50:65], v[186:189], v[208:211], v[50:65]
	v_exp_f32_e32 v103, v103
	v_cvt_pk_bf16_f32 v197, v100, v101
	v_add_f32_e32 v212, v212, v100
	v_add_f32_e32 v213, v213, v101
	v_exp_f32_e32 v104, v104
	v_mfma_f32_32x32x16_bf16 v[34:49], v[192:195], v[208:211], v[34:49]
	ds_read_b128 v[186:189], v221 offset:24576
	ds_read_b128 v[192:195], v221 offset:28672
	v_exp_f32_e32 v105, v105
	v_add_f32_e32 v212, v212, v102
	v_add_f32_e32 v213, v213, v103
	v_cvt_pk_bf16_f32 v198, v102, v103
	v_add_f32_e32 v212, v212, v104
	v_add_f32_e32 v213, v213, v105
	v_cvt_pk_bf16_f32 v199, v104, v105
	s_waitcnt lgkmcnt(7)
	v_mfma_f32_32x32x16_bf16 v[66:81], v[162:165], v[130:133], 0
	v_exp_f32_e32 v106, v106
	v_exp_f32_e32 v107, v107
	v_exp_f32_e32 v108, v108
	v_mfma_f32_32x32x16_bf16 v[82:97], v[162:165], v[146:149], 0
	ds_read_b128 v[162:165], v216 offset:49152
	v_exp_f32_e32 v109, v109
	v_cvt_pk_bf16_f32 v200, v106, v107
	v_add_f32_e32 v212, v212, v106
	v_add_f32_e32 v213, v213, v107
	v_exp_f32_e32 v110, v110
	s_waitcnt lgkmcnt(7)
	v_mfma_f32_32x32x16_bf16 v[66:81], v[166:169], v[134:137], v[66:81]
	v_exp_f32_e32 v111, v111
	v_cvt_pk_bf16_f32 v201, v108, v109
	v_add_f32_e32 v212, v212, v108
	v_add_f32_e32 v213, v213, v109
	v_exp_f32_e32 v112, v112
	v_mfma_f32_32x32x16_bf16 v[82:97], v[166:169], v[150:153], v[82:97]
	ds_read_b128 v[166:169], v217 offset:49152
	v_exp_f32_e32 v113, v113
	v_add_f32_e32 v212, v212, v110
	v_add_f32_e32 v213, v213, v111
	v_cvt_pk_bf16_f32 v202, v110, v111
	v_add_f32_e32 v212, v212, v112
	v_add_f32_e32 v213, v213, v113
	v_cvt_pk_bf16_f32 v203, v112, v113
	s_waitcnt lgkmcnt(5)
	v_mfma_f32_32x32x16_bf16 v[18:33], v[178:181], v[196:199], v[18:33]
	v_exp_f32_e32 v114, v114
	v_exp_f32_e32 v115, v115
	v_exp_f32_e32 v116, v116
	s_waitcnt lgkmcnt(4)
	v_mfma_f32_32x32x16_bf16 v[2:17], v[182:185], v[196:199], v[2:17]
	v_exp_f32_e32 v117, v117
	v_cvt_pk_bf16_f32 v204, v114, v115
	v_add_f32_e32 v214, v214, v114
	v_add_f32_e32 v215, v215, v115
	v_exp_f32_e32 v118, v118
	s_waitcnt lgkmcnt(3)
	v_mfma_f32_32x32x16_bf16 v[18:33], v[186:189], v[200:203], v[18:33]
	v_exp_f32_e32 v119, v119
	v_cvt_pk_bf16_f32 v205, v116, v117
	v_add_f32_e32 v214, v214, v116
	v_add_f32_e32 v215, v215, v117
	v_exp_f32_e32 v120, v120
	s_waitcnt lgkmcnt(2)
; DI f32x16 mfma32(bf16x8 a, bf16x8 b, f32x16 c) { return __builtin_amdgcn_mfma_f32_32x32x16_bf16(a, b, c, 0, 0, 0); }
; DI float fast_exp2(float x) { return __builtin_amdgcn_exp2f(x); }
; #define ATT_WRITE2(HALF, H) do { _Pragma("unroll") for (int j_ = 0; j_ < 2; ++j_) { \
;       char* sl_ = lds + (HALF) * 65536 + (2 * (H) + j_) * 16384; \
;       *(u32x4*)(sl_ + woff) = rk[j_]; \
;       *(u32x4*)(sl_ + 8192 + woff) = rv[j_]; } } while (0)
; template <bool NA, bool TRACK>
; DI void attn_item(char* lds, const bf16_t* P, bf16_t* Y, const bf16_t* vt, int rp, int q_off, int k1_off, int nt1,
;                   int vk1, int k2_off, int nt2, int vk2, int g_off, int y_off, int rlo, const float* rpb) {
;     ...
;       for (int j = 0; j < TPI; ++j) {
;         const char* Vs = Kb + j * 16384 + 8192;
;         if (j + 1 < TPI) ATT_QK(sn, j + 1);
;         float ps = 0.f;
; #pragma unroll
;         for (int kt = 0; kt < 2; ++kt) {
;           bf16x8 vf[4];
; #pragma unroll
;           for (int sp = 0; sp < 2; ++sp)
; #pragma unroll
;             for (int dm = 0; dm < 2; ++dm)
;               vf[sp * 2 + dm] = *(const bf16x8*)(Vs + (dm * 32 + r) * 128 + (((4 * kt + 2 * sp + h) ^ swz) << 4));
; #pragma unroll
;           for (int i = 0; i < 16; ++i) {
;             const float pv = fast_exp2(sc[kt][i]);
;             ps += pv;
;             sc[kt][i] = pv;
;           }
; #pragma unroll
;           for (int sp = 0; sp < 2; ++sp) {
;             u32x4 pu;
;             pu[0] = pk2(sc[kt][8 * sp + 0], sc[kt][8 * sp + 1]);
;             pu[1] = pk2(sc[kt][8 * sp + 2], sc[kt][8 * sp + 3]);
;             pu[2] = pk2(sc[kt][8 * sp + 4], sc[kt][8 * sp + 5]);
;             pu[3] = pk2(sc[kt][8 * sp + 6], sc[kt][8 * sp + 7]);
;             const bf16x8 pf = __builtin_bit_cast(bf16x8, pu);
; #pragma unroll
;             for (int dm = 0; dm < 2; ++dm) o[dm] = mfma32(vf[sp * 2 + dm], pf, o[dm]);
;           }
;         }
;         l_run += ps;
;         if (j + 1 < TPI) { sc[0] = sn[0]; sc[1] = sn[1]; }
;         if (j == 1 && more) { ATT_WRITE2(hb ^ 1, 0); ATT_LOAD2(it + 1, 1); }
;       }
;       if (more) ATT_WRITE2(hb ^ 1, 1);
	v_mfma_f32_32x32x16_bf16 v[2:17], v[192:195], v[200:203], v[2:17]
	v_exp_f32_e32 v121, v121
	v_add_f32_e32 v214, v214, v118
	v_add_f32_e32 v215, v215, v119
	v_cvt_pk_bf16_f32 v206, v118, v119
	v_add_f32_e32 v214, v214, v120
	v_add_f32_e32 v215, v215, v121
	v_cvt_pk_bf16_f32 v207, v120, v121
	v_mfma_f32_32x32x16_bf16 v[66:81], v[170:173], v[138:141], v[66:81]
	v_exp_f32_e32 v122, v122
	v_exp_f32_e32 v123, v123
	v_exp_f32_e32 v124, v124
	v_mfma_f32_32x32x16_bf16 v[82:97], v[170:173], v[154:157], v[82:97]
	ds_read_b128 v[170:173], v218 offset:49152
	v_exp_f32_e32 v125, v125
	v_cvt_pk_bf16_f32 v208, v122, v123
	v_add_f32_e32 v214, v214, v122
	v_add_f32_e32 v215, v215, v123
	v_exp_f32_e32 v126, v126
	v_mfma_f32_32x32x16_bf16 v[66:81], v[174:177], v[142:145], v[66:81]
	v_exp_f32_e32 v127, v127
	v_cvt_pk_bf16_f32 v209, v124, v125
	v_add_f32_e32 v214, v214, v124
	v_add_f32_e32 v215, v215, v125
	v_exp_f32_e32 v128, v128
	v_mfma_f32_32x32x16_bf16 v[82:97], v[174:177], v[158:161], v[82:97]
	ds_read_b128 v[174:177], v219 offset:49152
	v_exp_f32_e32 v129, v129
	v_add_f32_e32 v214, v214, v126
	v_add_f32_e32 v215, v215, v127
	v_cvt_pk_bf16_f32 v210, v126, v127
	v_add_f32_e32 v214, v214, v128
	v_add_f32_e32 v215, v215, v129
	v_cvt_pk_bf16_f32 v211, v128, v129
	v_mfma_f32_32x32x16_bf16 v[50:65], v[178:181], v[204:207], v[50:65]
	s_nop 1
	v_exp_f32_e32 v66, v66
	v_exp_f32_e32 v67, v67
	v_exp_f32_e32 v68, v68
	v_mfma_f32_32x32x16_bf16 v[34:49], v[182:185], v[204:207], v[34:49]
	ds_read_b128 v[178:181], v220 offset:40960
	ds_read_b128 v[182:185], v220 offset:45056
	v_exp_f32_e32 v69, v69
	v_cvt_pk_bf16_f32 v196, v66, v67
	v_add_f32_e32 v212, v212, v66
	v_add_f32_e32 v213, v213, v67
	v_exp_f32_e32 v70, v70
	v_mfma_f32_32x32x16_bf16 v[50:65], v[186:189], v[208:211], v[50:65]
	v_exp_f32_e32 v71, v71
	v_cvt_pk_bf16_f32 v197, v68, v69
	v_add_f32_e32 v212, v212, v68
	v_add_f32_e32 v213, v213, v69
	v_exp_f32_e32 v72, v72
	v_mfma_f32_32x32x16_bf16 v[34:49], v[192:195], v[208:211], v[34:49]
	ds_read_b128 v[186:189], v221 offset:40960
	ds_read_b128 v[192:195], v221 offset:45056
	v_exp_f32_e32 v73, v73
	v_add_f32_e32 v212, v212, v70
	v_add_f32_e32 v213, v213, v71
	v_cvt_pk_bf16_f32 v198, v70, v71
	v_add_f32_e32 v212, v212, v72
	v_add_f32_e32 v213, v213, v73
	v_cvt_pk_bf16_f32 v199, v72, v73
	s_waitcnt lgkmcnt(7)
	v_mfma_f32_32x32x16_bf16 v[98:113], v[162:165], v[130:133], 0
	v_exp_f32_e32 v74, v74
	v_exp_f32_e32 v75, v75
	v_exp_f32_e32 v76, v76
	v_mfma_f32_32x32x16_bf16 v[114:129], v[162:165], v[146:149], 0
	v_exp_f32_e32 v77, v77
	v_cvt_pk_bf16_f32 v200, v74, v75
	v_add_f32_e32 v212, v212, v74
	v_add_f32_e32 v213, v213, v75
	v_exp_f32_e32 v78, v78
	s_waitcnt lgkmcnt(6)
	v_mfma_f32_32x32x16_bf16 v[98:113], v[166:169], v[134:137], v[98:113]
	v_exp_f32_e32 v79, v79
	v_cvt_pk_bf16_f32 v201, v76, v77
	v_add_f32_e32 v212, v212, v76
	v_add_f32_e32 v213, v213, v77
	v_exp_f32_e32 v80, v80
	v_mfma_f32_32x32x16_bf16 v[114:129], v[166:169], v[150:153], v[114:129]
	v_exp_f32_e32 v81, v81
	v_add_f32_e32 v212, v212, v78
	v_add_f32_e32 v213, v213, v79
	v_cvt_pk_bf16_f32 v202, v78, v79
	v_add_f32_e32 v212, v212, v80
	v_add_f32_e32 v213, v213, v81
	v_cvt_pk_bf16_f32 v203, v80, v81
	s_waitcnt lgkmcnt(3)
	v_mfma_f32_32x32x16_bf16 v[18:33], v[178:181], v[196:199], v[18:33]
	v_exp_f32_e32 v82, v82
	v_exp_f32_e32 v83, v83
	v_exp_f32_e32 v84, v84
	s_waitcnt lgkmcnt(2)
	v_mfma_f32_32x32x16_bf16 v[2:17], v[182:185], v[196:199], v[2:17]
	v_exp_f32_e32 v85, v85
	v_cvt_pk_bf16_f32 v204, v82, v83
	v_add_f32_e32 v214, v214, v82
	v_add_f32_e32 v215, v215, v83
	v_exp_f32_e32 v86, v86
	s_waitcnt lgkmcnt(1)
	v_mfma_f32_32x32x16_bf16 v[18:33], v[186:189], v[200:203], v[18:33]
	v_exp_f32_e32 v87, v87
	v_cvt_pk_bf16_f32 v205, v84, v85
	v_add_f32_e32 v214, v214, v84
	v_add_f32_e32 v215, v215, v85
	v_exp_f32_e32 v88, v88
	s_waitcnt lgkmcnt(0)
	v_mfma_f32_32x32x16_bf16 v[2:17], v[192:195], v[200:203], v[2:17]
	v_exp_f32_e32 v89, v89
	v_add_f32_e32 v214, v214, v86
	v_add_f32_e32 v215, v215, v87
	v_cvt_pk_bf16_f32 v206, v86, v87
	v_add_f32_e32 v214, v214, v88
	v_add_f32_e32 v215, v215, v89
	v_cvt_pk_bf16_f32 v207, v88, v89
	v_mfma_f32_32x32x16_bf16 v[98:113], v[170:173], v[138:141], v[98:113]
	v_exp_f32_e32 v90, v90
	v_exp_f32_e32 v91, v91
	v_exp_f32_e32 v92, v92
	v_mfma_f32_32x32x16_bf16 v[114:129], v[170:173], v[154:157], v[114:129]
	v_exp_f32_e32 v93, v93
	v_cvt_pk_bf16_f32 v208, v90, v91
	v_add_f32_e32 v214, v214, v90
	v_add_f32_e32 v215, v215, v91
	v_exp_f32_e32 v94, v94
	v_mfma_f32_32x32x16_bf16 v[98:113], v[174:177], v[142:145], v[98:113]
	v_exp_f32_e32 v95, v95
	v_cvt_pk_bf16_f32 v209, v92, v93
	v_add_f32_e32 v214, v214, v92
	v_add_f32_e32 v215, v215, v93
	v_exp_f32_e32 v96, v96
	v_mfma_f32_32x32x16_bf16 v[114:129], v[174:177], v[158:161], v[114:129]
	v_exp_f32_e32 v97, v97
	v_add_f32_e32 v214, v214, v94
	v_add_f32_e32 v215, v215, v95
	v_cvt_pk_bf16_f32 v210, v94, v95
	v_add_f32_e32 v214, v214, v96
	v_add_f32_e32 v215, v215, v97
	v_cvt_pk_bf16_f32 v211, v96, v97
	v_mfma_f32_32x32x16_bf16 v[50:65], v[178:181], v[204:207], v[50:65]
	s_nop 1
	v_exp_f32_e32 v98, v98
	v_exp_f32_e32 v99, v99
	v_exp_f32_e32 v100, v100
	v_mfma_f32_32x32x16_bf16 v[34:49], v[182:185], v[204:207], v[34:49]
	ds_read_b128 v[178:181], v220 offset:57344
	ds_read_b128 v[182:185], v220 offset:61440
	v_exp_f32_e32 v101, v101
	v_cvt_pk_bf16_f32 v196, v98, v99
	v_add_f32_e32 v212, v212, v98
	v_add_f32_e32 v213, v213, v99
	v_exp_f32_e32 v102, v102
	v_mfma_f32_32x32x16_bf16 v[50:65], v[186:189], v[208:211], v[50:65]
	v_exp_f32_e32 v103, v103
	v_cvt_pk_bf16_f32 v197, v100, v101
	v_add_f32_e32 v212, v212, v100
	v_add_f32_e32 v213, v213, v101
	v_exp_f32_e32 v104, v104
	v_mfma_f32_32x32x16_bf16 v[34:49], v[192:195], v[208:211], v[34:49]
	ds_read_b128 v[186:189], v221 offset:57344
	ds_read_b128 v[192:195], v221 offset:61440
	v_exp_f32_e32 v105, v105
	v_add_f32_e32 v212, v212, v102
	v_add_f32_e32 v213, v213, v103
	v_cvt_pk_bf16_f32 v198, v102, v103
	v_add_f32_e32 v212, v212, v104
	v_add_f32_e32 v213, v213, v105
	v_cvt_pk_bf16_f32 v199, v104, v105
	s_add_i32 s18, s18, 1
	s_cmp_lt_i32 s18, s19
	s_cbranch_scc0 .Ldk_epi
; DI f32x16 mfma32(bf16x8 a, bf16x8 b, f32x16 c) { return __builtin_amdgcn_mfma_f32_32x32x16_bf16(a, b, c, 0, 0, 0); }
; DI float fast_exp2(float x) { return __builtin_amdgcn_exp2f(x); }
; template <bool NA, bool TRACK>
; DI void attn_item(char* lds, const bf16_t* P, bf16_t* Y, const bf16_t* vt, int rp, int q_off, int k1_off, int nt1,
;                   int vk1, int k2_off, int nt2, int vk2, int g_off, int y_off, int rlo, const float* rpb) {
;     ...
;   for (int it = 0; it < niter; ++it) {
;     const int hb = it & 1;
;     if constexpr (NA || TRACK) { if (it + 1 < niter) ATT_LOAD(it + 1); }
;     if constexpr (!NA && !TRACK) {
;     ...
;       const bool more = it + 1 < niter;
;       if (more) ATT_LOAD2(it + 1, 0);
;       const char* Kb = lds + hb * 65536;
;       f32x16 sc[2], sn[2];
;     ...
;       ATT_QK(sc, 0);
; #pragma unroll
;       for (int j = 0; j < TPI; ++j) {
;         const char* Vs = Kb + j * 16384 + 8192;
;         if (j + 1 < TPI) ATT_QK(sn, j + 1);
;         float ps = 0.f;
; #pragma unroll
;         for (int kt = 0; kt < 2; ++kt) {
;           bf16x8 vf[4];
; #pragma unroll
;           for (int sp = 0; sp < 2; ++sp)
; #pragma unroll
;             for (int dm = 0; dm < 2; ++dm)
;               vf[sp * 2 + dm] = *(const bf16x8*)(Vs + (dm * 32 + r) * 128 + (((4 * kt + 2 * sp + h) ^ swz) << 4));
; #pragma unroll
;           for (int i = 0; i < 16; ++i) {
;             const float pv = fast_exp2(sc[kt][i]);
;             ps += pv;
;             sc[kt][i] = pv;
;           }
; #pragma unroll
;           for (int sp = 0; sp < 2; ++sp) {
;             u32x4 pu;
;             pu[0] = pk2(sc[kt][8 * sp + 0], sc[kt][8 * sp + 1]);
;             pu[1] = pk2(sc[kt][8 * sp + 2], sc[kt][8 * sp + 3]);
;             pu[2] = pk2(sc[kt][8 * sp + 4], sc[kt][8 * sp + 5]);
;             pu[3] = pk2(sc[kt][8 * sp + 6], sc[kt][8 * sp + 7]);
;             const bf16x8 pf = __builtin_bit_cast(bf16x8, pu);
; #pragma unroll
;             for (int dm = 0; dm < 2; ++dm) o[dm] = mfma32(vf[sp * 2 + dm], pf, o[dm]);
;           }
;         }
;         l_run += ps;
;         if (j + 1 < TPI) { sc[0] = sn[0]; sc[1] = sn[1]; }
;         if (j == 1 && more) { ATT_WRITE2(hb ^ 1, 0); ATT_LOAD2(it + 1, 1); }
;       }
;       if (more) ATT_WRITE2(hb ^ 1, 1);
	s_waitcnt vmcnt(0)
	s_waitcnt lgkmcnt(0)
	s_barrier
	v_xor_b32_e32 v216, 0x10000, v216
	v_xor_b32_e32 v217, 0x10000, v217
	v_xor_b32_e32 v218, 0x10000, v218
	v_xor_b32_e32 v219, 0x10000, v219
	v_xor_b32_e32 v220, 0x10000, v220
	v_xor_b32_e32 v221, 0x10000, v221
	ds_read_b128 v[162:165], v216
	ds_read_b128 v[166:169], v217
	ds_read_b128 v[170:173], v218
	ds_read_b128 v[174:177], v219
	s_add_i32 s20, s18, 1
	s_cmp_ge_i32 s20, s19
	s_cbranch_scc1 .Ldk_skip_loop
	s_and_b32 s31, s20, 1
	s_lshl_b32 s31, s31, 16
	s_add_u32 s31, s31, s30
	s_lshl_b32 s20, s20, 2
	s_cmp_lt_i32 s20, s79
	s_cselect_b32 s21, 0, s79
	s_cselect_b32 s22, s4, s6
	s_cselect_b32 s23, s5, s7
	s_cselect_b32 s29, s90, 0x800
	s_sub_i32 s20, s20, s21
	s_mul_i32 s21, s20, 0x58000
	s_add_u32 s14, s22, s21
	s_addc_u32 s15, s23, 0
	s_lshl_b32 s20, s20, 6
	s_add_i32 s20, s20, s29
	s_lshl_b32 s20, s20, 1
	s_add_u32 s16, s8, s20
	s_addc_u32 s17, s9, 0
	s_add_u32 m0, s31, 0x0
	s_nop 0
	global_load_lds_dwordx4 v222, s[14:15]
	s_add_u32 m0, s31, 0x2000
	s_nop 0
	global_load_lds_dwordx4 v223, s[16:17]
	s_add_u32 s14, s14, 0x58000
	s_addc_u32 s15, s15, 0
	s_add_u32 s16, s16, 0x80
	s_addc_u32 s17, s17, 0
	s_add_u32 m0, s31, 0x4000
	s_nop 0
	global_load_lds_dwordx4 v222, s[14:15]
	s_add_u32 m0, s31, 0x6000
	s_nop 0
	global_load_lds_dwordx4 v223, s[16:17]
	s_add_u32 s14, s14, 0x58000
	s_addc_u32 s15, s15, 0
	s_add_u32 s16, s16, 0x80
	s_addc_u32 s17, s17, 0
	s_add_u32 m0, s31, 0x8000
	s_nop 0
	global_load_lds_dwordx4 v222, s[14:15]
	s_add_u32 m0, s31, 0xa000
	s_nop 0
	global_load_lds_dwordx4 v223, s[16:17]
	s_add_u32 s14, s14, 0x58000
	s_addc_u32 s15, s15, 0
	s_add_u32 s16, s16, 0x80
	s_addc_u32 s17, s17, 0
	s_add_u32 m0, s31, 0xc000
	s_nop 0
	global_load_lds_dwordx4 v222, s[14:15]
	s_add_u32 m0, s31, 0xe000
	s_nop 0
	global_load_lds_dwordx4 v223, s[16:17]
.Ldk_skip_loop:
	s_waitcnt lgkmcnt(3)
	v_mfma_f32_32x32x16_bf16 v[66:81], v[162:165], v[130:133], 0
	v_exp_f32_e32 v106, v106
	v_exp_f32_e32 v107, v107
	v_exp_f32_e32 v108, v108
	v_mfma_f32_32x32x16_bf16 v[82:97], v[162:165], v[146:149], 0
	ds_read_b128 v[162:165], v216 offset:16384
	v_exp_f32_e32 v109, v109
	v_cvt_pk_bf16_f32 v200, v106, v107
	v_add_f32_e32 v212, v212, v106
	v_add_f32_e32 v213, v213, v107
	v_exp_f32_e32 v110, v110
	s_waitcnt lgkmcnt(3)
	v_mfma_f32_32x32x16_bf16 v[66:81], v[166:169], v[134:137], v[66:81]
	v_exp_f32_e32 v111, v111
	v_cvt_pk_bf16_f32 v201, v108, v109
	v_add_f32_e32 v212, v212, v108
	v_add_f32_e32 v213, v213, v109
	v_exp_f32_e32 v112, v112
	v_mfma_f32_32x32x16_bf16 v[82:97], v[166:169], v[150:153], v[82:97]
	ds_read_b128 v[166:169], v217 offset:16384
	v_exp_f32_e32 v113, v113
	v_add_f32_e32 v212, v212, v110
	v_add_f32_e32 v213, v213, v111
	v_cvt_pk_bf16_f32 v202, v110, v111
	v_add_f32_e32 v212, v212, v112
	v_add_f32_e32 v213, v213, v113
	v_cvt_pk_bf16_f32 v203, v112, v113
	v_mfma_f32_32x32x16_bf16 v[18:33], v[178:181], v[196:199], v[18:33]
	v_exp_f32_e32 v114, v114
	v_exp_f32_e32 v115, v115
	v_exp_f32_e32 v116, v116
	v_mfma_f32_32x32x16_bf16 v[2:17], v[182:185], v[196:199], v[2:17]
	v_exp_f32_e32 v117, v117
	v_cvt_pk_bf16_f32 v204, v114, v115
	v_add_f32_e32 v214, v214, v114
	v_add_f32_e32 v215, v215, v115
	v_exp_f32_e32 v118, v118
	v_mfma_f32_32x32x16_bf16 v[18:33], v[186:189], v[200:203], v[18:33]
	v_exp_f32_e32 v119, v119
	v_cvt_pk_bf16_f32 v205, v116, v117
	v_add_f32_e32 v214, v214, v116
	v_add_f32_e32 v215, v215, v117
	v_exp_f32_e32 v120, v120
	v_mfma_f32_32x32x16_bf16 v[2:17], v[192:195], v[200:203], v[2:17]
	v_exp_f32_e32 v121, v121
	v_add_f32_e32 v214, v214, v118
	v_add_f32_e32 v215, v215, v119
	v_cvt_pk_bf16_f32 v206, v118, v119
	v_add_f32_e32 v214, v214, v120
	v_add_f32_e32 v215, v215, v121
	v_cvt_pk_bf16_f32 v207, v120, v121
	s_waitcnt lgkmcnt(3)
	v_mfma_f32_32x32x16_bf16 v[66:81], v[170:173], v[138:141], v[66:81]
	v_exp_f32_e32 v122, v122
	v_exp_f32_e32 v123, v123
	v_exp_f32_e32 v124, v124
	v_mfma_f32_32x32x16_bf16 v[82:97], v[170:173], v[154:157], v[82:97]
	ds_read_b128 v[170:173], v218 offset:16384
	v_exp_f32_e32 v125, v125
	v_cvt_pk_bf16_f32 v208, v122, v123
	v_add_f32_e32 v214, v214, v122
	v_add_f32_e32 v215, v215, v123
	v_exp_f32_e32 v126, v126
	s_waitcnt lgkmcnt(3)
	v_mfma_f32_32x32x16_bf16 v[66:81], v[174:177], v[142:145], v[66:81]
	v_exp_f32_e32 v127, v127
	v_cvt_pk_bf16_f32 v209, v124, v125
	v_add_f32_e32 v214, v214, v124
	v_add_f32_e32 v215, v215, v125
	v_exp_f32_e32 v128, v128
	v_mfma_f32_32x32x16_bf16 v[82:97], v[174:177], v[158:161], v[82:97]
	ds_read_b128 v[174:177], v219 offset:16384
	v_exp_f32_e32 v129, v129
	v_add_f32_e32 v214, v214, v126
	v_add_f32_e32 v215, v215, v127
	v_cvt_pk_bf16_f32 v210, v126, v127
	v_add_f32_e32 v214, v214, v128
	v_add_f32_e32 v215, v215, v129
	v_cvt_pk_bf16_f32 v211, v128, v129
	v_mfma_f32_32x32x16_bf16 v[50:65], v[178:181], v[204:207], v[50:65]
	s_nop 1
	v_exp_f32_e32 v66, v66
	v_exp_f32_e32 v67, v67
	v_exp_f32_e32 v68, v68
	v_mfma_f32_32x32x16_bf16 v[34:49], v[182:185], v[204:207], v[34:49]
	ds_read_b128 v[178:181], v220 offset:8192
	ds_read_b128 v[182:185], v220 offset:12288
	v_exp_f32_e32 v69, v69
	v_cvt_pk_bf16_f32 v196, v66, v67
	v_add_f32_e32 v212, v212, v66
	v_add_f32_e32 v213, v213, v67
	v_exp_f32_e32 v70, v70
	v_mfma_f32_32x32x16_bf16 v[50:65], v[186:189], v[208:211], v[50:65]
	v_exp_f32_e32 v71, v71
	v_cvt_pk_bf16_f32 v197, v68, v69
	v_add_f32_e32 v212, v212, v68
	v_add_f32_e32 v213, v213, v69
	v_exp_f32_e32 v72, v72
	v_mfma_f32_32x32x16_bf16 v[34:49], v[192:195], v[208:211], v[34:49]
	ds_read_b128 v[186:189], v221 offset:8192
	ds_read_b128 v[192:195], v221 offset:12288
	v_exp_f32_e32 v73, v73
	v_add_f32_e32 v212, v212, v70
	v_add_f32_e32 v213, v213, v71
	v_cvt_pk_bf16_f32 v198, v70, v71
	v_add_f32_e32 v212, v212, v72
	v_add_f32_e32 v213, v213, v73
	v_cvt_pk_bf16_f32 v199, v72, v73
	s_branch .Ldk_loop
; DI f32x16 mfma32(bf16x8 a, bf16x8 b, f32x16 c) { return __builtin_amdgcn_mfma_f32_32x32x16_bf16(a, b, c, 0, 0, 0); }
; DI float fast_exp2(float x) { return __builtin_amdgcn_exp2f(x); }
; #define ATT_WRITE2(HALF, H) do { _Pragma("unroll") for (int j_ = 0; j_ < 2; ++j_) { \
;       char* sl_ = lds + (HALF) * 65536 + (2 * (H) + j_) * 16384; \
;       *(u32x4*)(sl_ + woff) = rk[j_]; \
;       *(u32x4*)(sl_ + 8192 + woff) = rv[j_]; } } while (0)
; template <bool NA, bool TRACK>
; DI void attn_item(char* lds, const bf16_t* P, bf16_t* Y, const bf16_t* vt, int rp, int q_off, int k1_off, int nt1,
;                   int vk1, int k2_off, int nt2, int vk2, int g_off, int y_off, int rlo, const float* rpb) {
;     ...
;   u32x2 gate[2][4];
; #pragma unroll
;   for (int dm = 0; dm < 2; ++dm)
; #pragma unroll
;     for (int g = 0; g < 4; ++g)
;       gate[dm][g] = *(const u32x2*)(P + g_off + (size_t)(w * 32 + r) * INW + dm * 32 + 8 * g + 4 * h);
;     ...
;           for (int i = 0; i < 16; ++i) {
;             const float pv = fast_exp2(sc[kt][i]);
;             ps += pv;
;             sc[kt][i] = pv;
;           }
; #pragma unroll
;           for (int sp = 0; sp < 2; ++sp) {
;             u32x4 pu;
;             pu[0] = pk2(sc[kt][8 * sp + 0], sc[kt][8 * sp + 1]);
;             pu[1] = pk2(sc[kt][8 * sp + 2], sc[kt][8 * sp + 3]);
;             pu[2] = pk2(sc[kt][8 * sp + 4], sc[kt][8 * sp + 5]);
;             pu[3] = pk2(sc[kt][8 * sp + 6], sc[kt][8 * sp + 7]);
;             const bf16x8 pf = __builtin_bit_cast(bf16x8, pu);
; #pragma unroll
;             for (int dm = 0; dm < 2; ++dm) o[dm] = mfma32(vf[sp * 2 + dm], pf, o[dm]);
;           }
;         }
;         l_run += ps;
;         if (j + 1 < TPI) { sc[0] = sn[0]; sc[1] = sn[1]; }
;         if (j == 1 && more) { ATT_WRITE2(hb ^ 1, 0); ATT_LOAD2(it + 1, 1); }
;       }
;       if (more) ATT_WRITE2(hb ^ 1, 1);
.Ldk_epi:
	v_exp_f32_e32 v106, v106
	v_exp_f32_e32 v107, v107
	v_exp_f32_e32 v108, v108
	s_waitcnt lgkmcnt(3)
	v_mfma_f32_32x32x16_bf16 v[18:33], v[178:181], v[196:199], v[18:33]
	v_exp_f32_e32 v109, v109
	v_cvt_pk_bf16_f32 v200, v106, v107
	v_add_f32_e32 v212, v212, v106
	v_add_f32_e32 v213, v213, v107
	v_exp_f32_e32 v110, v110
	s_waitcnt lgkmcnt(2)
	v_mfma_f32_32x32x16_bf16 v[2:17], v[182:185], v[196:199], v[2:17]
	v_exp_f32_e32 v111, v111
	v_cvt_pk_bf16_f32 v201, v108, v109
	v_add_f32_e32 v212, v212, v108
	v_add_f32_e32 v213, v213, v109
	v_exp_f32_e32 v112, v112
	v_exp_f32_e32 v113, v113
	v_add_f32_e32 v212, v212, v110
	v_add_f32_e32 v213, v213, v111
	v_cvt_pk_bf16_f32 v202, v110, v111
	v_add_f32_e32 v212, v212, v112
	v_add_f32_e32 v213, v213, v113
	v_cvt_pk_bf16_f32 v203, v112, v113
	v_exp_f32_e32 v114, v114
	v_exp_f32_e32 v115, v115
	v_exp_f32_e32 v116, v116
	s_waitcnt lgkmcnt(1)
	v_mfma_f32_32x32x16_bf16 v[18:33], v[186:189], v[200:203], v[18:33]
	v_exp_f32_e32 v117, v117
	v_cvt_pk_bf16_f32 v204, v114, v115
	v_add_f32_e32 v214, v214, v114
	v_add_f32_e32 v215, v215, v115
	v_exp_f32_e32 v118, v118
	s_waitcnt lgkmcnt(0)
	v_mfma_f32_32x32x16_bf16 v[2:17], v[192:195], v[200:203], v[2:17]
	v_exp_f32_e32 v119, v119
	v_cvt_pk_bf16_f32 v205, v116, v117
	v_add_f32_e32 v214, v214, v116
	v_add_f32_e32 v215, v215, v117
	v_exp_f32_e32 v120, v120
	v_exp_f32_e32 v121, v121
	v_add_f32_e32 v214, v214, v118
	v_add_f32_e32 v215, v215, v119
	v_cvt_pk_bf16_f32 v206, v118, v119
	v_add_f32_e32 v214, v214, v120
	v_add_f32_e32 v215, v215, v121
	v_cvt_pk_bf16_f32 v207, v120, v121
	v_exp_f32_e32 v122, v122
	v_exp_f32_e32 v123, v123
	v_exp_f32_e32 v124, v124
	v_mfma_f32_32x32x16_bf16 v[50:65], v[178:181], v[204:207], v[50:65]
	v_exp_f32_e32 v125, v125
	v_cvt_pk_bf16_f32 v208, v122, v123
	v_add_f32_e32 v214, v214, v122
	v_add_f32_e32 v215, v215, v123
	v_exp_f32_e32 v126, v126
	v_mfma_f32_32x32x16_bf16 v[34:49], v[182:185], v[204:207], v[34:49]
	v_exp_f32_e32 v127, v127
	v_cvt_pk_bf16_f32 v209, v124, v125
	v_add_f32_e32 v214, v214, v124
	v_add_f32_e32 v215, v215, v125
	v_exp_f32_e32 v128, v128
	v_exp_f32_e32 v129, v129
	v_add_f32_e32 v214, v214, v126
	v_add_f32_e32 v215, v215, v127
	v_cvt_pk_bf16_f32 v210, v126, v127
	v_add_f32_e32 v214, v214, v128
	v_add_f32_e32 v215, v215, v129
	v_cvt_pk_bf16_f32 v211, v128, v129
	s_nop 1
	v_mfma_f32_32x32x16_bf16 v[50:65], v[186:189], v[208:211], v[50:65]
	v_mfma_f32_32x32x16_bf16 v[34:49], v[192:195], v[208:211], v[34:49]
	s_waitcnt vmcnt(0)
	s_waitcnt lgkmcnt(0)
	s_barrier
	v_bfe_u32 v147, v251, 5, 1
	v_ashrrev_i32_e32 v0, 1, v251
	s_movk_i32 s0, 0xffe0
	v_bfi_b32 v146, s0, v0, v251
	v_lshlrev_b32_e32 v138, 3, v147
	v_mov_b32_e32 v150, s28
	v_mov_b32_e32 v148, v232
	v_mov_b32_e32 v149, v233
	v_mov_b32_e32 v144, v234
	v_mov_b32_e32 v145, v235
	v_mov_b32_e32 v142, v236
	v_mov_b32_e32 v143, v237
	v_mov_b32_e32 v140, v238
	v_mov_b32_e32 v141, v239
	v_mov_b32_e32 v136, v242
	v_mov_b32_e32 v137, v243
	v_mov_b32_e32 v134, v244
	v_mov_b32_e32 v135, v245
	v_mov_b32_e32 v132, v226
	v_mov_b32_e32 v133, v227
	v_mov_b32_e32 v130, v224
	v_mov_b32_e32 v131, v225
	v_lshlrev_b32_e32 v226, 4, v240
	v_add_u32_e32 v228, s39, v226
	v_add_u32_e32 v229, s40, v226
	v_add_f32_e32 v212, v212, v213
	v_add_f32_e32 v214, v214, v215
	s_cmp_eq_u32 s38, 0
	s_cbranch_scc0 .Ldk_x1
	ds_write_b128 v228, v[34:37]
	ds_write_b128 v228, v[38:41] offset:1024
	ds_write_b128 v228, v[42:45] offset:2048
	ds_write_b128 v228, v[46:49] offset:3072
	ds_write_b128 v228, v[50:53] offset:4096
	ds_write_b128 v228, v[54:57] offset:5120
	ds_write_b128 v228, v[58:61] offset:6144
	ds_write_b128 v228, v[62:65] offset:7168
	ds_write_b32 v228, v214 offset:8192
	s_branch .Ldk_x2
